# MODE_IN/MODE_UP epilogue blocks padded so every 8-byte instruction is 8-byte aligned
# baseline (speedup 1.0000x reference)
; __device__ __forceinline__ float sigm(float v) { return __builtin_amdgcn_rcpf(1.0f + __builtin_amdgcn_exp2f(-1.44269504089f * v)); }
; __device__ __forceinline__ u32x4 pack8(const f32x4& v0, const f32x4& v1) { u32x4 w; w.x = cvt_pk_bf16(v0[0], v0[1]); w.y = cvt_pk_bf16(v0[2], v0[3]); w.z = cvt_pk_bf16(v1[0], v1[1]); w.w = cvt_pk_bf16(v1[2], v1[3]); return w; }
; template <int ACT> __device__ __forceinline__ void epi_act_store(f32x4 (&acc)[2][2][4][2], const float (&rs)[2][4], bf16_t* out, int ld, int row0, int col0, float* ssqv_slot, bool want_ssq, int fq) {
;     ...
;         for (int m = 0; m < 4; ++m) { const int row = row0 + ai * 128 + m * 16; float sq = 0.f;
; #pragma unroll
;             for (int bj = 0; bj < 2; ++bj) { f32x4 v0 = acc[ai][bj][m][0] * rs[ai][m], v1 = acc[ai][bj][m][1] * rs[ai][m];
;                 if (ACT == 1) { f32x2 a = gelu_pk((f32x2){v0[0], v0[1]}), b = gelu_pk((f32x2){v0[2], v0[3]}), c = gelu_pk((f32x2){v1[0], v1[1]}), d = gelu_pk((f32x2){v1[2], v1[3]});
;                     v0 = (f32x4){a.x, a.y, b.x, b.y}; v1 = (f32x4){c.x, c.y, d.x, d.y}; sq += sumsq8(v0, v1); }
;                 if (ACT == 2) {
; #pragma unroll
;                     for (int e = 0; e < 4; ++e) { v0[e] = sigm(v0[e]); v1[e] = sigm(v1[e]); } }
;                 *(u32x4*)(out + (size_t)row * ld + col0 + bj * 128) = pack8(v0, v1); }
;             if (ACT == 1) { if (want_ssq) { sq += __shfl_xor(sq, 16); sq += __shfl_xor(sq, 32); if (fq == 0) ssqv_slot[row] = sq; } } }
; }
; __device__ __forceinline__ void epi_run(const Epi& E, f32x4 (&acc)[2][2][4][2], const Unit& u, int wr, int wc, int fr, int fq) {
;     const int mode = u.mode;
;     const int row0 = u.pm * 256 + wr * 64 + fr, col0 = u.pn * 256 + wc * 32 + 8 * fq;
;     if (mode == MODE_IN || mode == MODE_UP) {
;         float rs[2][4]; epi_rstd(E.ssq_in, row0, fq, rs);
;         if (mode == MODE_UP) { epi_act_store<0>(acc, rs, E.out16, E.ld16, row0, col0, nullptr, false, fq); return; }
;         const int atype = u.pn >> 2;
;         if (atype == 2) epi_act_store<1>(acc, rs, E.Z, NIN, row0, col0, E.ssqv + (size_t)((u.pn - 8) * 4 + wc) * M, true, fq);
;         else epi_act_store<0>(acc, rs, E.Z, NIN, row0, col0, nullptr, false, fq);
.Lmy_rstd_join:
	s_cbranch_scc0 .LBB0_349
	s_and_b32 s2, s23, -4
	s_cmp_lg_u32 s2, 8
	s_cbranch_scc0 .LBB0_330
	s_waitcnt lgkmcnt(0)
	v_lshrrev_b32_e32 v214, 2, v201
	v_and_b32_e32 v215, 3, v201
	v_lshl_add_u32 v216, v215, 4, v214
	v_lshlrev_b32_e32 v216, 2, v216
	v_and_b32_e32 v217, -16, v239
	v_or_b32_e32 v217, v217, v214
	s_nop 0
	v_lshl_add_u32 v217, s95, 8, v217
	v_and_b32_e32 v218, 0xffffffe7, v242
	v_lshl_or_b32 v218, v215, 3, v218
	v_lshl_or_b32 v218, s23, 8, v218
	v_mul_lo_u32 v222, v217, s69
	v_lshl_add_u32 v222, v218, 1, v222
	v_mov_b32_e32 v223, 0
	s_nop 0
	v_lshl_add_u64 v[220:221], v[222:223], 0, s[70:71]
	s_lshl_b32 s96, s69, 4
	s_mov_b32 s97, 0
	s_mul_i32 s44, s69, 0x50
	s_mov_b32 s45, 0
	s_nop 0
	v_pk_mul_f32 v[126:127], v[126:127], v[130:131] op_sel_hi:[1,0]
	v_pk_mul_f32 v[128:129], v[128:129], v[130:131] op_sel_hi:[1,0]
	v_pk_mul_f32 v[122:123], v[122:123], v[130:131] op_sel_hi:[1,0]
	v_pk_mul_f32 v[124:125], v[124:125], v[130:131] op_sel_hi:[1,0]
	v_cvt_pk_bf16_f32 v126, v126, v127
	v_cvt_pk_bf16_f32 v127, v128, v129
	v_cvt_pk_bf16_f32 v128, v122, v123
	v_cvt_pk_bf16_f32 v129, v124, v125
	ds_bpermute_b32 v224, v216, v126
	ds_bpermute_b32 v225, v216, v127
	ds_bpermute_b32 v226, v216, v128
	ds_bpermute_b32 v227, v216, v129
	v_pk_mul_f32 v[118:119], v[118:119], v[130:131] op_sel_hi:[1,0]
	v_pk_mul_f32 v[120:121], v[120:121], v[130:131] op_sel_hi:[1,0]
	v_pk_mul_f32 v[114:115], v[114:115], v[130:131] op_sel_hi:[1,0]
	v_pk_mul_f32 v[116:117], v[116:117], v[130:131] op_sel_hi:[1,0]
	v_cvt_pk_bf16_f32 v118, v118, v119
	v_cvt_pk_bf16_f32 v119, v120, v121
	v_cvt_pk_bf16_f32 v120, v114, v115
	v_cvt_pk_bf16_f32 v121, v116, v117
	ds_bpermute_b32 v228, v216, v118
	ds_bpermute_b32 v229, v216, v119
	ds_bpermute_b32 v230, v216, v120
	ds_bpermute_b32 v231, v216, v121
	s_waitcnt lgkmcnt(4)
	s_nop 0
	global_store_dwordx4 v[220:221], v[224:227], off
	v_pk_mul_f32 v[110:111], v[110:111], v[0:1] op_sel_hi:[1,0]
	v_pk_mul_f32 v[112:113], v[112:113], v[0:1] op_sel_hi:[1,0]
	v_pk_mul_f32 v[106:107], v[106:107], v[0:1] op_sel_hi:[1,0]
	v_pk_mul_f32 v[108:109], v[108:109], v[0:1] op_sel_hi:[1,0]
	v_cvt_pk_bf16_f32 v110, v110, v111
	v_cvt_pk_bf16_f32 v111, v112, v113
	v_cvt_pk_bf16_f32 v112, v106, v107
	v_cvt_pk_bf16_f32 v113, v108, v109
	ds_bpermute_b32 v224, v216, v110
	ds_bpermute_b32 v225, v216, v111
	ds_bpermute_b32 v226, v216, v112
	ds_bpermute_b32 v227, v216, v113
	s_waitcnt lgkmcnt(4)
	s_nop 0
	global_store_dwordx4 v[220:221], v[228:231], off offset:256
	v_lshl_add_u64 v[220:221], v[220:221], 0, s[96:97]
	v_pk_mul_f32 v[102:103], v[102:103], v[0:1] op_sel_hi:[1,0]
	v_pk_mul_f32 v[104:105], v[104:105], v[0:1] op_sel_hi:[1,0]
	v_pk_mul_f32 v[94:95], v[94:95], v[0:1] op_sel_hi:[1,0]
	v_pk_mul_f32 v[96:97], v[96:97], v[0:1] op_sel_hi:[1,0]
	v_cvt_pk_bf16_f32 v102, v102, v103
	v_cvt_pk_bf16_f32 v103, v104, v105
	v_cvt_pk_bf16_f32 v104, v94, v95
	v_cvt_pk_bf16_f32 v105, v96, v97
	ds_bpermute_b32 v228, v216, v102
	ds_bpermute_b32 v229, v216, v103
	ds_bpermute_b32 v230, v216, v104
	ds_bpermute_b32 v231, v216, v105
	s_waitcnt lgkmcnt(4)
	s_nop 0
	global_store_dwordx4 v[220:221], v[224:227], off
	v_pk_mul_f32 v[98:99], v[98:99], v[132:133] op_sel_hi:[1,0]
	v_pk_mul_f32 v[100:101], v[100:101], v[132:133] op_sel_hi:[1,0]
	v_pk_mul_f32 v[90:91], v[90:91], v[132:133] op_sel_hi:[1,0]
	v_pk_mul_f32 v[92:93], v[92:93], v[132:133] op_sel_hi:[1,0]
	v_cvt_pk_bf16_f32 v98, v98, v99
	v_cvt_pk_bf16_f32 v99, v100, v101
	v_cvt_pk_bf16_f32 v100, v90, v91
	v_cvt_pk_bf16_f32 v101, v92, v93
	ds_bpermute_b32 v224, v216, v98
	ds_bpermute_b32 v225, v216, v99
	ds_bpermute_b32 v226, v216, v100
	ds_bpermute_b32 v227, v216, v101
	s_waitcnt lgkmcnt(4)
	s_nop 0
	global_store_dwordx4 v[220:221], v[228:231], off offset:256
	v_lshl_add_u64 v[220:221], v[220:221], 0, s[96:97]
	v_pk_mul_f32 v[86:87], v[86:87], v[132:133] op_sel_hi:[1,0]
	v_pk_mul_f32 v[88:89], v[88:89], v[132:133] op_sel_hi:[1,0]
	v_pk_mul_f32 v[78:79], v[78:79], v[132:133] op_sel_hi:[1,0]
	v_pk_mul_f32 v[80:81], v[80:81], v[132:133] op_sel_hi:[1,0]
	v_cvt_pk_bf16_f32 v86, v86, v87
	v_cvt_pk_bf16_f32 v87, v88, v89
	v_cvt_pk_bf16_f32 v88, v78, v79
	v_cvt_pk_bf16_f32 v89, v80, v81
	ds_bpermute_b32 v228, v216, v86
	ds_bpermute_b32 v229, v216, v87
	ds_bpermute_b32 v230, v216, v88
	ds_bpermute_b32 v231, v216, v89
	s_waitcnt lgkmcnt(4)
	s_nop 0
	global_store_dwordx4 v[220:221], v[224:227], off
	v_pk_mul_f32 v[82:83], v[82:83], v[142:143] op_sel_hi:[1,0]
	v_pk_mul_f32 v[84:85], v[84:85], v[142:143] op_sel_hi:[1,0]
	v_pk_mul_f32 v[74:75], v[74:75], v[142:143] op_sel_hi:[1,0]
	v_pk_mul_f32 v[76:77], v[76:77], v[142:143] op_sel_hi:[1,0]
	v_cvt_pk_bf16_f32 v82, v82, v83
	v_cvt_pk_bf16_f32 v83, v84, v85
	v_cvt_pk_bf16_f32 v84, v74, v75
	v_cvt_pk_bf16_f32 v85, v76, v77
	ds_bpermute_b32 v224, v216, v82
	ds_bpermute_b32 v225, v216, v83
	ds_bpermute_b32 v226, v216, v84
	ds_bpermute_b32 v227, v216, v85
	s_waitcnt lgkmcnt(4)
	s_nop 0
	global_store_dwordx4 v[220:221], v[228:231], off offset:256
	v_lshl_add_u64 v[220:221], v[220:221], 0, s[96:97]
	v_pk_mul_f32 v[70:71], v[70:71], v[142:143] op_sel_hi:[1,0]
	v_pk_mul_f32 v[72:73], v[72:73], v[142:143] op_sel_hi:[1,0]
	v_pk_mul_f32 v[66:67], v[66:67], v[142:143] op_sel_hi:[1,0]
	v_pk_mul_f32 v[68:69], v[68:69], v[142:143] op_sel_hi:[1,0]
	v_cvt_pk_bf16_f32 v70, v70, v71
	v_cvt_pk_bf16_f32 v71, v72, v73
	v_cvt_pk_bf16_f32 v72, v66, v67
	v_cvt_pk_bf16_f32 v73, v68, v69
	ds_bpermute_b32 v228, v216, v70
	ds_bpermute_b32 v229, v216, v71
	ds_bpermute_b32 v230, v216, v72
	ds_bpermute_b32 v231, v216, v73
	s_waitcnt lgkmcnt(4)
; __device__ __forceinline__ float sigm(float v) { return __builtin_amdgcn_rcpf(1.0f + __builtin_amdgcn_exp2f(-1.44269504089f * v)); }
; __device__ __forceinline__ u32x4 pack8(const f32x4& v0, const f32x4& v1) { u32x4 w; w.x = cvt_pk_bf16(v0[0], v0[1]); w.y = cvt_pk_bf16(v0[2], v0[3]); w.z = cvt_pk_bf16(v1[0], v1[1]); w.w = cvt_pk_bf16(v1[2], v1[3]); return w; }
; __device__ __forceinline__ float sumsq8(const f32x4& v0, const f32x4& v1) { return (v0[0] * v0[0] + v0[1] * v0[1]) + (v0[2] * v0[2] + v0[3] * v0[3]) + (v1[0] * v1[0] + v1[1] * v1[1]) + (v1[2] * v1[2] + v1[3] * v1[3]); }
; template <int ACT> __device__ __forceinline__ void epi_act_store(f32x4 (&acc)[2][2][4][2], const float (&rs)[2][4], bf16_t* out, int ld, int row0, int col0, float* ssqv_slot, bool want_ssq, int fq) {
;     ...
;         for (int m = 0; m < 4; ++m) { const int row = row0 + ai * 128 + m * 16; float sq = 0.f;
; #pragma unroll
;             for (int bj = 0; bj < 2; ++bj) { f32x4 v0 = acc[ai][bj][m][0] * rs[ai][m], v1 = acc[ai][bj][m][1] * rs[ai][m];
;                 if (ACT == 1) { f32x2 a = gelu_pk((f32x2){v0[0], v0[1]}), b = gelu_pk((f32x2){v0[2], v0[3]}), c = gelu_pk((f32x2){v1[0], v1[1]}), d = gelu_pk((f32x2){v1[2], v1[3]});
;                     v0 = (f32x4){a.x, a.y, b.x, b.y}; v1 = (f32x4){c.x, c.y, d.x, d.y}; sq += sumsq8(v0, v1); }
;                 if (ACT == 2) {
; #pragma unroll
;                     for (int e = 0; e < 4; ++e) { v0[e] = sigm(v0[e]); v1[e] = sigm(v1[e]); } }
;                 *(u32x4*)(out + (size_t)row * ld + col0 + bj * 128) = pack8(v0, v1); }
	s_nop 0
	global_store_dwordx4 v[220:221], v[224:227], off
	v_pk_mul_f32 v[62:63], v[62:63], v[140:141] op_sel_hi:[1,0]
	v_pk_mul_f32 v[64:65], v[64:65], v[140:141] op_sel_hi:[1,0]
	v_pk_mul_f32 v[58:59], v[58:59], v[140:141] op_sel_hi:[1,0]
	v_pk_mul_f32 v[60:61], v[60:61], v[140:141] op_sel_hi:[1,0]
	v_cvt_pk_bf16_f32 v62, v62, v63
	v_cvt_pk_bf16_f32 v63, v64, v65
	v_cvt_pk_bf16_f32 v64, v58, v59
	v_cvt_pk_bf16_f32 v65, v60, v61
	ds_bpermute_b32 v224, v216, v62
	ds_bpermute_b32 v225, v216, v63
	ds_bpermute_b32 v226, v216, v64
	ds_bpermute_b32 v227, v216, v65
	s_waitcnt lgkmcnt(4)
	s_nop 0
	global_store_dwordx4 v[220:221], v[228:231], off offset:256
	v_lshl_add_u64 v[220:221], v[220:221], 0, s[44:45]
	v_pk_mul_f32 v[54:55], v[54:55], v[140:141] op_sel_hi:[1,0]
	v_pk_mul_f32 v[56:57], v[56:57], v[140:141] op_sel_hi:[1,0]
	v_pk_mul_f32 v[50:51], v[50:51], v[140:141] op_sel_hi:[1,0]
	v_pk_mul_f32 v[52:53], v[52:53], v[140:141] op_sel_hi:[1,0]
	v_cvt_pk_bf16_f32 v54, v54, v55
	v_cvt_pk_bf16_f32 v55, v56, v57
	v_cvt_pk_bf16_f32 v56, v50, v51
	v_cvt_pk_bf16_f32 v57, v52, v53
	ds_bpermute_b32 v228, v216, v54
	ds_bpermute_b32 v229, v216, v55
	ds_bpermute_b32 v230, v216, v56
	ds_bpermute_b32 v231, v216, v57
	s_waitcnt lgkmcnt(4)
	s_nop 0
	global_store_dwordx4 v[220:221], v[224:227], off
	v_pk_mul_f32 v[46:47], v[46:47], v[138:139] op_sel_hi:[1,0]
	v_pk_mul_f32 v[48:49], v[48:49], v[138:139] op_sel_hi:[1,0]
	v_pk_mul_f32 v[42:43], v[42:43], v[138:139] op_sel_hi:[1,0]
	v_pk_mul_f32 v[44:45], v[44:45], v[138:139] op_sel_hi:[1,0]
	v_cvt_pk_bf16_f32 v46, v46, v47
	v_cvt_pk_bf16_f32 v47, v48, v49
	v_cvt_pk_bf16_f32 v48, v42, v43
	v_cvt_pk_bf16_f32 v49, v44, v45
	ds_bpermute_b32 v224, v216, v46
	ds_bpermute_b32 v225, v216, v47
	ds_bpermute_b32 v226, v216, v48
	ds_bpermute_b32 v227, v216, v49
	s_waitcnt lgkmcnt(4)
	s_nop 0
	global_store_dwordx4 v[220:221], v[228:231], off offset:256
	v_lshl_add_u64 v[220:221], v[220:221], 0, s[96:97]
	v_pk_mul_f32 v[38:39], v[38:39], v[138:139] op_sel_hi:[1,0]
	v_pk_mul_f32 v[40:41], v[40:41], v[138:139] op_sel_hi:[1,0]
	v_pk_mul_f32 v[34:35], v[34:35], v[138:139] op_sel_hi:[1,0]
	v_pk_mul_f32 v[36:37], v[36:37], v[138:139] op_sel_hi:[1,0]
	v_cvt_pk_bf16_f32 v38, v38, v39
	v_cvt_pk_bf16_f32 v39, v40, v41
	v_cvt_pk_bf16_f32 v40, v34, v35
	v_cvt_pk_bf16_f32 v41, v36, v37
	ds_bpermute_b32 v228, v216, v38
	ds_bpermute_b32 v229, v216, v39
	ds_bpermute_b32 v230, v216, v40
	ds_bpermute_b32 v231, v216, v41
	s_waitcnt lgkmcnt(4)
	s_nop 0
	global_store_dwordx4 v[220:221], v[224:227], off
	v_pk_mul_f32 v[30:31], v[30:31], v[134:135] op_sel_hi:[1,0]
	v_pk_mul_f32 v[32:33], v[32:33], v[134:135] op_sel_hi:[1,0]
	v_pk_mul_f32 v[26:27], v[26:27], v[134:135] op_sel_hi:[1,0]
	v_pk_mul_f32 v[28:29], v[28:29], v[134:135] op_sel_hi:[1,0]
	v_cvt_pk_bf16_f32 v30, v30, v31
	v_cvt_pk_bf16_f32 v31, v32, v33
	v_cvt_pk_bf16_f32 v32, v26, v27
	v_cvt_pk_bf16_f32 v33, v28, v29
	ds_bpermute_b32 v224, v216, v30
	ds_bpermute_b32 v225, v216, v31
	ds_bpermute_b32 v226, v216, v32
	ds_bpermute_b32 v227, v216, v33
	s_waitcnt lgkmcnt(4)
	s_nop 0
	global_store_dwordx4 v[220:221], v[228:231], off offset:256
	v_lshl_add_u64 v[220:221], v[220:221], 0, s[96:97]
	v_pk_mul_f32 v[22:23], v[22:23], v[134:135] op_sel_hi:[1,0]
	v_pk_mul_f32 v[24:25], v[24:25], v[134:135] op_sel_hi:[1,0]
	v_pk_mul_f32 v[18:19], v[18:19], v[134:135] op_sel_hi:[1,0]
	v_pk_mul_f32 v[20:21], v[20:21], v[134:135] op_sel_hi:[1,0]
	v_cvt_pk_bf16_f32 v22, v22, v23
	v_cvt_pk_bf16_f32 v23, v24, v25
	v_cvt_pk_bf16_f32 v24, v18, v19
	v_cvt_pk_bf16_f32 v25, v20, v21
	ds_bpermute_b32 v228, v216, v22
	ds_bpermute_b32 v229, v216, v23
	ds_bpermute_b32 v230, v216, v24
	ds_bpermute_b32 v231, v216, v25
	s_waitcnt lgkmcnt(4)
	s_nop 0
	global_store_dwordx4 v[220:221], v[224:227], off
	v_pk_mul_f32 v[14:15], v[14:15], v[136:137] op_sel_hi:[1,0]
	v_pk_mul_f32 v[16:17], v[16:17], v[136:137] op_sel_hi:[1,0]
	v_pk_mul_f32 v[10:11], v[10:11], v[136:137] op_sel_hi:[1,0]
	v_pk_mul_f32 v[12:13], v[12:13], v[136:137] op_sel_hi:[1,0]
	v_cvt_pk_bf16_f32 v14, v14, v15
	v_cvt_pk_bf16_f32 v15, v16, v17
	v_cvt_pk_bf16_f32 v16, v10, v11
	v_cvt_pk_bf16_f32 v17, v12, v13
	ds_bpermute_b32 v224, v216, v14
	ds_bpermute_b32 v225, v216, v15
	ds_bpermute_b32 v226, v216, v16
	ds_bpermute_b32 v227, v216, v17
	s_waitcnt lgkmcnt(4)
	s_nop 0
	global_store_dwordx4 v[220:221], v[228:231], off offset:256
	v_lshl_add_u64 v[220:221], v[220:221], 0, s[96:97]
	v_pk_mul_f32 v[6:7], v[6:7], v[136:137] op_sel_hi:[1,0]
	v_pk_mul_f32 v[8:9], v[8:9], v[136:137] op_sel_hi:[1,0]
	v_pk_mul_f32 v[2:3], v[2:3], v[136:137] op_sel_hi:[1,0]
	v_pk_mul_f32 v[4:5], v[4:5], v[136:137] op_sel_hi:[1,0]
	v_cvt_pk_bf16_f32 v6, v6, v7
	v_cvt_pk_bf16_f32 v7, v8, v9
	v_cvt_pk_bf16_f32 v8, v2, v3
	v_cvt_pk_bf16_f32 v9, v4, v5
	ds_bpermute_b32 v228, v216, v6
	ds_bpermute_b32 v229, v216, v7
	ds_bpermute_b32 v230, v216, v8
	ds_bpermute_b32 v231, v216, v9
	s_waitcnt lgkmcnt(4)
	s_nop 0
	global_store_dwordx4 v[220:221], v[224:227], off
	s_waitcnt lgkmcnt(0)
	s_nop 0
	global_store_dwordx4 v[220:221], v[228:231], off offset:256
	s_mov_b64 s[8:9], 0
; __device__ __forceinline__ float sumsq8(const f32x4& v0, const f32x4& v1) { return (v0[0] * v0[0] + v0[1] * v0[1]) + (v0[2] * v0[2] + v0[3] * v0[3]) + (v1[0] * v1[0] + v1[1] * v1[1]) + (v1[2] * v1[2] + v1[3] * v1[3]); }
; __device__ __forceinline__ f32x2 gelu_pk(f32x2 v) {
;     const f32x2 av = __builtin_elementwise_abs(v), d = av * 0.2316418882f + 1.0f;
;     f32x2 t; t.x = __builtin_amdgcn_rcpf(d.x); t.y = __builtin_amdgcn_rcpf(d.y);
;     f32x2 q = t * 0.5307027145f + (-0.7265760135f); q = q * t + 0.7107068705f; q = q * t + (-0.142248368f); q = q * t + 0.127414796f; q = q * t;
;     const f32x2 s = (v * v) * (-0.72134752044f);
;     f32x2 e; e.x = __builtin_amdgcn_exp2f(s.x); e.y = __builtin_amdgcn_exp2f(s.y);
;     const f32x2 m = v * (q * e), r = v - m;
;     f32x2 o; o.x = v.x < 0.f ? m.x : r.x; o.y = v.y < 0.f ? m.y : r.y; return o;
; }
; template <int ACT> __device__ __forceinline__ void epi_act_store(f32x4 (&acc)[2][2][4][2], const float (&rs)[2][4], bf16_t* out, int ld, int row0, int col0, float* ssqv_slot, bool want_ssq, int fq) {
;     ...
;         for (int m = 0; m < 4; ++m) { const int row = row0 + ai * 128 + m * 16; float sq = 0.f;
; #pragma unroll
;             for (int bj = 0; bj < 2; ++bj) { f32x4 v0 = acc[ai][bj][m][0] * rs[ai][m], v1 = acc[ai][bj][m][1] * rs[ai][m];
;                 if (ACT == 1) { f32x2 a = gelu_pk((f32x2){v0[0], v0[1]}), b = gelu_pk((f32x2){v0[2], v0[3]}), c = gelu_pk((f32x2){v1[0], v1[1]}), d = gelu_pk((f32x2){v1[2], v1[3]});
;                     v0 = (f32x4){a.x, a.y, b.x, b.y}; v1 = (f32x4){c.x, c.y, d.x, d.y}; sq += sumsq8(v0, v1); }
.LBB0_330:
	s_andn2_b64 vcc, exec, s[8:9]
	s_cbranch_vccnz .LBB0_348
	s_nop 0
	v_lshrrev_b32_e32 v168, 2, v201
	v_and_b32_e32 v169, 3, v201
	v_lshl_add_u32 v167, v169, 4, v168
	v_lshlrev_b32_e32 v167, 2, v167
	v_and_b32_e32 v170, 15, v201
	v_sub_u32_e32 v168, v168, v170
	v_lshrrev_b32_e32 v170, 4, v201
	v_sub_u32_e32 v169, v169, v170
	v_lshlrev_b32_e32 v169, 4, v169
	v_mul_lo_u32 v168, v168, s69
	v_add_u32_e32 v180, v168, v169
	v_ashrrev_i32_e32 v181, 31, v180
	v_pk_mul_f32 v[154:155], v[126:127], v[130:131] op_sel_hi:[1,0]
	s_lshl_b32 s2, s23, 16
	v_and_b32_e32 v149, 0x7fffffff, v155
	v_and_b32_e32 v148, 0x7fffffff, v154
	v_pk_fma_f32 v[148:149], v[148:149], s[14:15], 1.0 op_sel_hi:[1,0,0]
	v_readlane_b32 s8, v250, 30
	v_rcp_f32_e32 v158, v148
	v_rcp_f32_e32 v159, v149
	s_add_i32 s30, s8, s2
	s_mov_b32 s2, 0xbf3a00e3
	v_mov_b64_e32 v[148:149], s[2:3]
	v_pk_mul_f32 v[162:163], v[154:155], v[154:155]
	v_pk_fma_f32 v[160:161], v[158:159], s[38:39], v[148:149] op_sel_hi:[1,0,0]
	v_pk_mul_f32 v[162:163], v[162:163], s[18:19] op_sel_hi:[1,0]
	v_pk_fma_f32 v[160:161], v[158:159], v[160:161], s[10:11] op_sel_hi:[1,1,0]
	v_exp_f32_e32 v162, v162
	v_exp_f32_e32 v163, v163
	v_pk_fma_f32 v[160:161], v[158:159], v[160:161], s[56:57] op_sel_hi:[1,1,0]
	v_pk_mul_f32 v[152:153], v[128:129], v[130:131] op_sel_hi:[1,0]
	v_pk_fma_f32 v[160:161], v[158:159], v[160:161], s[64:65] op_sel_hi:[1,1,0]
	v_cmp_gt_f32_e32 vcc, 0, v154
	v_pk_mul_f32 v[158:159], v[158:159], v[160:161]
	v_pk_mul_f32 v[160:161], v[152:153], v[152:153]
	v_pk_mul_f32 v[158:159], v[162:163], v[158:159]
	v_pk_mul_f32 v[156:157], v[122:123], v[130:131] op_sel_hi:[1,0]
	v_pk_mul_f32 v[162:163], v[154:155], v[158:159]
	v_pk_fma_f32 v[158:159], v[154:155], v[158:159], v[154:155] neg_lo:[1,0,0] neg_hi:[1,0,0]
	v_and_b32_e32 v154, 0x7fffffff, v152
	v_cndmask_b32_e32 v135, v158, v162, vcc
	v_cmp_gt_f32_e32 vcc, 0, v155
	v_and_b32_e32 v155, 0x7fffffff, v153
	v_pk_fma_f32 v[154:155], v[154:155], s[14:15], 1.0 op_sel_hi:[1,0,0]
	v_cndmask_b32_e32 v137, v159, v163, vcc
	v_rcp_f32_e32 v154, v154
	v_rcp_f32_e32 v155, v155
	v_cmp_gt_f32_e32 vcc, 0, v152
	v_pk_mul_f32 v[150:151], v[124:125], v[130:131] op_sel_hi:[1,0]
	s_lshl_b64 s[8:9], s[30:31], 2
	v_pk_fma_f32 v[158:159], v[154:155], s[38:39], v[148:149] op_sel_hi:[1,0,0]
	v_readlane_b32 s20, v250, 5
	v_pk_fma_f32 v[158:159], v[154:155], v[158:159], s[10:11] op_sel_hi:[1,1,0]
	v_mov_b32_e32 v213, v1
	v_pk_fma_f32 v[158:159], v[154:155], v[158:159], s[56:57] op_sel_hi:[1,1,0]
	v_readlane_b32 s21, v250, 6
	v_pk_fma_f32 v[158:159], v[154:155], v[158:159], s[64:65] op_sel_hi:[1,1,0]
	s_add_u32 s20, s20, s8
	v_pk_mul_f32 v[154:155], v[154:155], v[158:159]
	v_pk_mul_f32 v[158:159], v[160:161], s[18:19] op_sel_hi:[1,0]
	v_lshl_add_u64 v[146:147], v[212:213], 1, s[70:71]
	v_exp_f32_e32 v158, v158
	v_exp_f32_e32 v159, v159
	s_addc_u32 s21, s21, s9
	v_mad_i64_i32 v[144:145], s[8:9], v210, s69, v[146:147]
	v_pk_mul_f32 v[154:155], v[158:159], v[154:155]
	s_nop 0
	v_pk_mul_f32 v[158:159], v[152:153], v[154:155]
	v_pk_fma_f32 v[154:155], v[152:153], v[154:155], v[152:153] neg_lo:[1,0,0] neg_hi:[1,0,0]
	v_and_b32_e32 v152, 0x7fffffff, v156
	v_cndmask_b32_e32 v139, v154, v158, vcc
	v_cmp_gt_f32_e32 vcc, 0, v153
	v_and_b32_e32 v153, 0x7fffffff, v157
	v_pk_fma_f32 v[152:153], v[152:153], s[14:15], 1.0 op_sel_hi:[1,0,0]
	v_cndmask_b32_e32 v141, v155, v159, vcc
	v_rcp_f32_e32 v152, v152
	v_rcp_f32_e32 v153, v153
	v_pk_mul_f32 v[158:159], v[156:157], v[156:157]
	v_cmp_gt_f32_e32 vcc, 0, v156
	v_pk_mul_f32 v[158:159], v[158:159], s[18:19] op_sel_hi:[1,0]
	v_pk_fma_f32 v[154:155], v[152:153], s[38:39], v[148:149] op_sel_hi:[1,0,0]
	v_exp_f32_e32 v158, v158
	v_pk_fma_f32 v[154:155], v[152:153], v[154:155], s[10:11] op_sel_hi:[1,1,0]
	v_exp_f32_e32 v159, v159
	v_pk_fma_f32 v[154:155], v[152:153], v[154:155], s[56:57] op_sel_hi:[1,1,0]
	s_nop 0
	v_pk_fma_f32 v[154:155], v[152:153], v[154:155], s[64:65] op_sel_hi:[1,1,0]
	s_nop 0
	v_pk_mul_f32 v[152:153], v[152:153], v[154:155]
	v_pk_mul_f32 v[154:155], v[150:151], v[150:151]
	v_pk_mul_f32 v[152:153], v[158:159], v[152:153]
	v_pk_mul_f32 v[154:155], v[154:155], s[18:19] op_sel_hi:[1,0]
	v_pk_mul_f32 v[158:159], v[156:157], v[152:153]
	v_pk_fma_f32 v[152:153], v[156:157], v[152:153], v[156:157] neg_lo:[1,0,0] neg_hi:[1,0,0]
	v_exp_f32_e32 v154, v154
	v_cndmask_b32_e32 v143, v152, v158, vcc
	v_cmp_gt_f32_e32 vcc, 0, v157
	v_and_b32_e32 v152, 0x7fffffff, v150
	v_exp_f32_e32 v155, v155
	v_cndmask_b32_e32 v158, v153, v159, vcc
	v_and_b32_e32 v153, 0x7fffffff, v151
	v_pk_fma_f32 v[152:153], v[152:153], s[14:15], 1.0 op_sel_hi:[1,0,0]
	v_cmp_gt_f32_e32 vcc, 0, v150
	v_rcp_f32_e32 v152, v152
	v_rcp_f32_e32 v153, v153
	s_nop 0
	v_pk_fma_f32 v[156:157], v[152:153], s[38:39], v[148:149] op_sel_hi:[1,0,0]
	s_nop 0
	v_pk_fma_f32 v[156:157], v[152:153], v[156:157], s[10:11] op_sel_hi:[1,1,0]
	s_nop 0
	v_pk_fma_f32 v[156:157], v[152:153], v[156:157], s[56:57] op_sel_hi:[1,1,0]
	s_nop 0
	v_pk_fma_f32 v[156:157], v[152:153], v[156:157], s[64:65] op_sel_hi:[1,1,0]
	s_nop 0
	v_pk_mul_f32 v[152:153], v[152:153], v[156:157]
	v_pk_mul_f32 v[156:157], v[114:115], v[130:131] op_sel_hi:[1,0]
	v_pk_mul_f32 v[152:153], v[154:155], v[152:153]
	s_nop 0
	v_pk_mul_f32 v[154:155], v[150:151], v[152:153]
	v_pk_fma_f32 v[152:153], v[150:151], v[152:153], v[150:151] neg_lo:[1,0,0] neg_hi:[1,0,0]
	v_mul_f32_e32 v150, v137, v137
	v_cndmask_b32_e32 v154, v152, v154, vcc
	v_cmp_gt_f32_e32 vcc, 0, v151
	v_mul_f32_e32 v151, v141, v141
	v_fmac_f32_e32 v150, v135, v135
	v_fmac_f32_e32 v151, v139, v139
	v_add_f32_e32 v150, v150, v151
	v_mul_f32_e32 v151, v158, v158
; __device__ __forceinline__ float sigm(float v) { return __builtin_amdgcn_rcpf(1.0f + __builtin_amdgcn_exp2f(-1.44269504089f * v)); }
; __device__ __forceinline__ u32x4 pack8(const f32x4& v0, const f32x4& v1) { u32x4 w; w.x = cvt_pk_bf16(v0[0], v0[1]); w.y = cvt_pk_bf16(v0[2], v0[3]); w.z = cvt_pk_bf16(v1[0], v1[1]); w.w = cvt_pk_bf16(v1[2], v1[3]); return w; }
; __device__ __forceinline__ float sumsq8(const f32x4& v0, const f32x4& v1) { return (v0[0] * v0[0] + v0[1] * v0[1]) + (v0[2] * v0[2] + v0[3] * v0[3]) + (v1[0] * v1[0] + v1[1] * v1[1]) + (v1[2] * v1[2] + v1[3] * v1[3]); }
; template <int ACT> __device__ __forceinline__ void epi_act_store(f32x4 (&acc)[2][2][4][2], const float (&rs)[2][4], bf16_t* out, int ld, int row0, int col0, float* ssqv_slot, bool want_ssq, int fq) {
;     ...
;         for (int m = 0; m < 4; ++m) { const int row = row0 + ai * 128 + m * 16; float sq = 0.f;
; #pragma unroll
;             for (int bj = 0; bj < 2; ++bj) { f32x4 v0 = acc[ai][bj][m][0] * rs[ai][m], v1 = acc[ai][bj][m][1] * rs[ai][m];
;                 if (ACT == 1) { f32x2 a = gelu_pk((f32x2){v0[0], v0[1]}), b = gelu_pk((f32x2){v0[2], v0[3]}), c = gelu_pk((f32x2){v1[0], v1[1]}), d = gelu_pk((f32x2){v1[2], v1[3]});
;                     v0 = (f32x4){a.x, a.y, b.x, b.y}; v1 = (f32x4){c.x, c.y, d.x, d.y}; sq += sumsq8(v0, v1); }
;                 if (ACT == 2) {
; #pragma unroll
;                     for (int e = 0; e < 4; ++e) { v0[e] = sigm(v0[e]); v1[e] = sigm(v1[e]); } }
;                 *(u32x4*)(out + (size_t)row * ld + col0 + bj * 128) = pack8(v0, v1); }
;             if (ACT == 1) { if (want_ssq) { sq += __shfl_xor(sq, 16); sq += __shfl_xor(sq, 32); if (fq == 0) ssqv_slot[row] = sq; } } }
	v_cndmask_b32_e32 v153, v153, v155, vcc
	v_fmac_f32_e32 v151, v143, v143
	v_add_f32_e32 v150, v151, v150
	v_mul_f32_e32 v151, v153, v153
	v_fmac_f32_e32 v151, v154, v154
	v_cvt_pk_bf16_f32 v153, v154, v153
	v_pk_mul_f32 v[154:155], v[118:119], v[130:131] op_sel_hi:[1,0]
	v_cvt_pk_bf16_f32 v152, v143, v158
	v_and_b32_e32 v159, 0x7fffffff, v155
	v_and_b32_e32 v158, 0x7fffffff, v154
	v_pk_fma_f32 v[158:159], v[158:159], s[14:15], 1.0 op_sel_hi:[1,0,0]
	v_pk_mul_f32 v[162:163], v[154:155], v[154:155]
	v_rcp_f32_e32 v158, v158
	v_rcp_f32_e32 v159, v159
	v_pk_mul_f32 v[162:163], v[162:163], s[18:19] op_sel_hi:[1,0]
	v_add_f32_e32 v164, v151, v150
	v_exp_f32_e32 v162, v162
	v_pk_fma_f32 v[160:161], v[158:159], s[38:39], v[148:149] op_sel_hi:[1,0,0]
	v_exp_f32_e32 v163, v163
	v_pk_fma_f32 v[160:161], v[158:159], v[160:161], s[10:11] op_sel_hi:[1,1,0]
	v_cvt_pk_bf16_f32 v150, v135, v137
	v_pk_fma_f32 v[160:161], v[158:159], v[160:161], s[56:57] op_sel_hi:[1,1,0]
	v_cvt_pk_bf16_f32 v151, v139, v141
	v_pk_fma_f32 v[160:161], v[158:159], v[160:161], s[64:65] op_sel_hi:[1,1,0]
	v_lshl_add_u64 v[176:177], v[144:145], 0, v[180:181]
	ds_bpermute_b32 v168, v167, v150
	ds_bpermute_b32 v169, v167, v151
	ds_bpermute_b32 v170, v167, v152
	ds_bpermute_b32 v171, v167, v153
	v_pk_mul_f32 v[158:159], v[158:159], v[160:161]
	v_cmp_gt_f32_e32 vcc, 0, v154
	v_pk_mul_f32 v[158:159], v[162:163], v[158:159]
	v_pk_mul_f32 v[152:153], v[120:121], v[130:131] op_sel_hi:[1,0]
	v_pk_mul_f32 v[162:163], v[154:155], v[158:159]
	v_pk_fma_f32 v[158:159], v[154:155], v[158:159], v[154:155] neg_lo:[1,0,0] neg_hi:[1,0,0]
	v_and_b32_e32 v154, 0x7fffffff, v152
	v_cndmask_b32_e32 v135, v158, v162, vcc
	v_cmp_gt_f32_e32 vcc, 0, v155
	v_and_b32_e32 v155, 0x7fffffff, v153
	v_pk_fma_f32 v[154:155], v[154:155], s[14:15], 1.0 op_sel_hi:[1,0,0]
	v_cndmask_b32_e32 v137, v159, v163, vcc
	v_rcp_f32_e32 v154, v154
	v_rcp_f32_e32 v155, v155
	v_pk_mul_f32 v[160:161], v[152:153], v[152:153]
	v_cmp_gt_f32_e32 vcc, 0, v152
	v_pk_mul_f32 v[150:151], v[116:117], v[130:131] op_sel_hi:[1,0]
	v_pk_fma_f32 v[158:159], v[154:155], s[38:39], v[148:149] op_sel_hi:[1,0,0]
	s_nop 0
	v_pk_fma_f32 v[158:159], v[154:155], v[158:159], s[10:11] op_sel_hi:[1,1,0]
	s_nop 0
	v_pk_fma_f32 v[158:159], v[154:155], v[158:159], s[56:57] op_sel_hi:[1,1,0]
	s_nop 0
	v_pk_fma_f32 v[158:159], v[154:155], v[158:159], s[64:65] op_sel_hi:[1,1,0]
	s_nop 0
	v_pk_mul_f32 v[154:155], v[154:155], v[158:159]
	v_pk_mul_f32 v[158:159], v[160:161], s[18:19] op_sel_hi:[1,0]
	s_nop 0
	v_exp_f32_e32 v158, v158
	v_exp_f32_e32 v159, v159
	s_nop 0
	v_pk_mul_f32 v[154:155], v[158:159], v[154:155]
	s_nop 0
	v_pk_mul_f32 v[158:159], v[152:153], v[154:155]
	v_pk_fma_f32 v[154:155], v[152:153], v[154:155], v[152:153] neg_lo:[1,0,0] neg_hi:[1,0,0]
	v_and_b32_e32 v152, 0x7fffffff, v156
	v_cndmask_b32_e32 v139, v154, v158, vcc
	v_cmp_gt_f32_e32 vcc, 0, v153
	v_and_b32_e32 v153, 0x7fffffff, v157
	v_pk_fma_f32 v[152:153], v[152:153], s[14:15], 1.0 op_sel_hi:[1,0,0]
	v_cndmask_b32_e32 v141, v155, v159, vcc
	v_rcp_f32_e32 v152, v152
	v_rcp_f32_e32 v153, v153
	v_pk_mul_f32 v[158:159], v[156:157], v[156:157]
	v_cmp_gt_f32_e32 vcc, 0, v156
	v_pk_mul_f32 v[158:159], v[158:159], s[18:19] op_sel_hi:[1,0]
	v_pk_fma_f32 v[154:155], v[152:153], s[38:39], v[148:149] op_sel_hi:[1,0,0]
	v_exp_f32_e32 v158, v158
	v_pk_fma_f32 v[154:155], v[152:153], v[154:155], s[10:11] op_sel_hi:[1,1,0]
	v_exp_f32_e32 v159, v159
	v_pk_fma_f32 v[154:155], v[152:153], v[154:155], s[56:57] op_sel_hi:[1,1,0]
	s_nop 0
	v_pk_fma_f32 v[154:155], v[152:153], v[154:155], s[64:65] op_sel_hi:[1,1,0]
	s_nop 0
	v_pk_mul_f32 v[152:153], v[152:153], v[154:155]
	v_pk_mul_f32 v[154:155], v[150:151], v[150:151]
	v_pk_mul_f32 v[152:153], v[158:159], v[152:153]
	s_nop 0
	v_pk_mul_f32 v[158:159], v[156:157], v[152:153]
	v_pk_fma_f32 v[152:153], v[156:157], v[152:153], v[156:157] neg_lo:[1,0,0] neg_hi:[1,0,0]
	s_nop 0
	v_cndmask_b32_e32 v143, v152, v158, vcc
	v_cmp_gt_f32_e32 vcc, 0, v157
	v_and_b32_e32 v152, 0x7fffffff, v150
	s_nop 0
	v_cndmask_b32_e32 v156, v153, v159, vcc
	v_and_b32_e32 v153, 0x7fffffff, v151
	v_pk_fma_f32 v[152:153], v[152:153], s[14:15], 1.0 op_sel_hi:[1,0,0]
	v_cmp_gt_f32_e32 vcc, 0, v150
	v_rcp_f32_e32 v152, v152
	v_rcp_f32_e32 v153, v153
	s_nop 0
	v_pk_fma_f32 v[148:149], v[152:153], s[38:39], v[148:149] op_sel_hi:[1,0,0]
	s_nop 0
	v_pk_fma_f32 v[148:149], v[152:153], v[148:149], s[10:11] op_sel_hi:[1,1,0]
	s_nop 0
	v_pk_fma_f32 v[148:149], v[152:153], v[148:149], s[56:57] op_sel_hi:[1,1,0]
	s_nop 0
	v_pk_fma_f32 v[148:149], v[152:153], v[148:149], s[64:65] op_sel_hi:[1,1,0]
	s_nop 0
	v_pk_mul_f32 v[148:149], v[152:153], v[148:149]
	v_pk_mul_f32 v[152:153], v[154:155], s[18:19] op_sel_hi:[1,0]
	s_nop 0
	v_exp_f32_e32 v152, v152
	v_exp_f32_e32 v153, v153
	s_nop 0
	v_pk_mul_f32 v[148:149], v[152:153], v[148:149]
	s_nop 0
	v_pk_mul_f32 v[152:153], v[150:151], v[148:149]
	v_pk_fma_f32 v[148:149], v[150:151], v[148:149], v[150:151] neg_lo:[1,0,0] neg_hi:[1,0,0]
	v_cvt_pk_bf16_f32 v150, v143, v156
	v_cndmask_b32_e32 v152, v148, v152, vcc
	v_cmp_gt_f32_e32 vcc, 0, v151
	v_mul_f32_e32 v148, v137, v137
	v_fmac_f32_e32 v148, v135, v135
	v_cndmask_b32_e32 v151, v149, v153, vcc
	v_mul_f32_e32 v149, v141, v141
	v_fmac_f32_e32 v149, v139, v139
	v_add_f32_e32 v148, v148, v149
	v_mul_f32_e32 v149, v156, v156
	v_fmac_f32_e32 v149, v143, v143
	v_add_f32_e32 v148, v149, v148
	v_mul_f32_e32 v149, v151, v151
	v_fmac_f32_e32 v149, v152, v152
	v_add_f32_e32 v148, v149, v148
	v_add_f32_e32 v153, v164, v148
	v_cvt_pk_bf16_f32 v148, v135, v137
	ds_bpermute_b32 v135, v133, v153
	v_cvt_pk_bf16_f32 v149, v139, v141
	v_cvt_pk_bf16_f32 v151, v152, v151
	s_waitcnt lgkmcnt(0)
	global_store_dwordx4 v[176:177], v[168:171], off
	v_lshl_add_u64 v[178:179], v[144:145], 0, v[180:181]
	ds_bpermute_b32 v172, v167, v148
	ds_bpermute_b32 v173, v167, v149
	ds_bpermute_b32 v174, v167, v150
	ds_bpermute_b32 v175, v167, v151
	v_lshl_add_u64 v[144:145], v[210:211], 2, s[20:21]
	s_waitcnt lgkmcnt(0)
	v_add_f32_e32 v135, v153, v135
	ds_bpermute_b32 v137, v131, v135
	s_and_saveexec_b64 s[8:9], s[40:41]
	s_cbranch_execz .LBB0_333
	s_waitcnt lgkmcnt(0)
	v_add_f32_e32 v135, v135, v137
	global_store_dword v[144:145], v135, off

; __device__ __forceinline__ float sigm(float v) { return __builtin_amdgcn_rcpf(1.0f + __builtin_amdgcn_exp2f(-1.44269504089f * v)); }
; __device__ __forceinline__ u32x4 pack8(const f32x4& v0, const f32x4& v1) { u32x4 w; w.x = cvt_pk_bf16(v0[0], v0[1]); w.y = cvt_pk_bf16(v0[2], v0[3]); w.z = cvt_pk_bf16(v1[0], v1[1]); w.w = cvt_pk_bf16(v1[2], v1[3]); return w; }
; __device__ __forceinline__ float sumsq8(const f32x4& v0, const f32x4& v1) { return (v0[0] * v0[0] + v0[1] * v0[1]) + (v0[2] * v0[2] + v0[3] * v0[3]) + (v1[0] * v1[0] + v1[1] * v1[1]) + (v1[2] * v1[2] + v1[3] * v1[3]); }
; template <int ACT> __device__ __forceinline__ void epi_act_store(f32x4 (&acc)[2][2][4][2], const float (&rs)[2][4], bf16_t* out, int ld, int row0, int col0, float* ssqv_slot, bool want_ssq, int fq) {
;     ...
;         for (int m = 0; m < 4; ++m) { const int row = row0 + ai * 128 + m * 16; float sq = 0.f;
; #pragma unroll
;             for (int bj = 0; bj < 2; ++bj) { f32x4 v0 = acc[ai][bj][m][0] * rs[ai][m], v1 = acc[ai][bj][m][1] * rs[ai][m];
;                 if (ACT == 1) { f32x2 a = gelu_pk((f32x2){v0[0], v0[1]}), b = gelu_pk((f32x2){v0[2], v0[3]}), c = gelu_pk((f32x2){v1[0], v1[1]}), d = gelu_pk((f32x2){v1[2], v1[3]});
;                     v0 = (f32x4){a.x, a.y, b.x, b.y}; v1 = (f32x4){c.x, c.y, d.x, d.y}; sq += sumsq8(v0, v1); }
;                 if (ACT == 2) {
; #pragma unroll
;                     for (int e = 0; e < 4; ++e) { v0[e] = sigm(v0[e]); v1[e] = sigm(v1[e]); } }
;                 *(u32x4*)(out + (size_t)row * ld + col0 + bj * 128) = pack8(v0, v1); }
;             if (ACT == 1) { if (want_ssq) { sq += __shfl_xor(sq, 16); sq += __shfl_xor(sq, 32); if (fq == 0) ssqv_slot[row] = sq; } } }
; }
; __device__ __forceinline__ void epi_run(const Epi& E, f32x4 (&acc)[2][2][4][2], const Unit& u, int wr, int wc, int fr, int fq) {
;     const int mode = u.mode;
;     const int row0 = u.pm * 256 + wr * 64 + fr, col0 = u.pn * 256 + wc * 32 + 8 * fq;
;     if (mode == MODE_IN || mode == MODE_UP) {
;         float rs[2][4]; epi_rstd(E.ssq_in, row0, fq, rs);
;         if (mode == MODE_UP) { epi_act_store<0>(acc, rs, E.out16, E.ld16, row0, col0, nullptr, false, fq); return; }
.LBB0_349:
	s_andn2_b64 vcc, exec, s[8:9]
	s_cbranch_vccnz .LBB0_351
	s_waitcnt lgkmcnt(0)
	v_lshrrev_b32_e32 v214, 2, v201
	v_and_b32_e32 v215, 3, v201
	v_lshl_add_u32 v216, v215, 4, v214
	v_lshlrev_b32_e32 v216, 2, v216
	v_and_b32_e32 v217, -16, v239
	v_or_b32_e32 v217, v217, v214
	s_nop 0
	v_lshl_add_u32 v217, s95, 8, v217
	v_and_b32_e32 v218, 0xffffffe7, v242
	v_lshl_or_b32 v218, v215, 3, v218
	v_lshl_or_b32 v218, s23, 8, v218
	v_mul_lo_u32 v222, v217, s86
	v_add_u32_e32 v222, v222, v218
	v_mov_b32_e32 v223, 0
	v_lshl_add_u64 v[220:221], v[222:223], 1, s[70:71]
	s_lshl_b32 s8, s86, 5
	s_mov_b32 s9, 0
	s_mul_i32 s44, s86, 0xa0
	s_mov_b32 s45, 0
	s_nop 0
	v_pk_mul_f32 v[126:127], v[126:127], v[130:131] op_sel_hi:[1,0]
	v_pk_mul_f32 v[128:129], v[128:129], v[130:131] op_sel_hi:[1,0]
	v_pk_mul_f32 v[122:123], v[122:123], v[130:131] op_sel_hi:[1,0]
	v_pk_mul_f32 v[124:125], v[124:125], v[130:131] op_sel_hi:[1,0]
	v_cvt_pk_bf16_f32 v126, v126, v127
	v_cvt_pk_bf16_f32 v127, v128, v129
	v_cvt_pk_bf16_f32 v128, v122, v123
	v_cvt_pk_bf16_f32 v129, v124, v125
	ds_bpermute_b32 v224, v216, v126
	ds_bpermute_b32 v225, v216, v127
	ds_bpermute_b32 v226, v216, v128
	ds_bpermute_b32 v227, v216, v129
	v_pk_mul_f32 v[118:119], v[118:119], v[130:131] op_sel_hi:[1,0]
	v_pk_mul_f32 v[120:121], v[120:121], v[130:131] op_sel_hi:[1,0]
	v_pk_mul_f32 v[114:115], v[114:115], v[130:131] op_sel_hi:[1,0]
	v_pk_mul_f32 v[116:117], v[116:117], v[130:131] op_sel_hi:[1,0]
	v_cvt_pk_bf16_f32 v118, v118, v119
	v_cvt_pk_bf16_f32 v119, v120, v121
	v_cvt_pk_bf16_f32 v120, v114, v115
	v_cvt_pk_bf16_f32 v121, v116, v117
	ds_bpermute_b32 v228, v216, v118
	ds_bpermute_b32 v229, v216, v119
	ds_bpermute_b32 v230, v216, v120
	ds_bpermute_b32 v231, v216, v121
	s_waitcnt lgkmcnt(4)
	s_nop 0
	global_store_dwordx4 v[220:221], v[224:227], off
	v_pk_mul_f32 v[110:111], v[110:111], v[0:1] op_sel_hi:[1,0]
	v_pk_mul_f32 v[112:113], v[112:113], v[0:1] op_sel_hi:[1,0]
	v_pk_mul_f32 v[106:107], v[106:107], v[0:1] op_sel_hi:[1,0]
	v_pk_mul_f32 v[108:109], v[108:109], v[0:1] op_sel_hi:[1,0]
	v_cvt_pk_bf16_f32 v110, v110, v111
	v_cvt_pk_bf16_f32 v111, v112, v113
	v_cvt_pk_bf16_f32 v112, v106, v107
	v_cvt_pk_bf16_f32 v113, v108, v109
	ds_bpermute_b32 v224, v216, v110
	ds_bpermute_b32 v225, v216, v111
	ds_bpermute_b32 v226, v216, v112
	ds_bpermute_b32 v227, v216, v113
	s_waitcnt lgkmcnt(4)
	s_nop 0
	global_store_dwordx4 v[220:221], v[228:231], off offset:256
	v_lshl_add_u64 v[220:221], v[220:221], 0, s[8:9]
	v_pk_mul_f32 v[102:103], v[102:103], v[0:1] op_sel_hi:[1,0]
	v_pk_mul_f32 v[104:105], v[104:105], v[0:1] op_sel_hi:[1,0]
	v_pk_mul_f32 v[94:95], v[94:95], v[0:1] op_sel_hi:[1,0]
	v_pk_mul_f32 v[96:97], v[96:97], v[0:1] op_sel_hi:[1,0]
	v_cvt_pk_bf16_f32 v102, v102, v103
	v_cvt_pk_bf16_f32 v103, v104, v105
	v_cvt_pk_bf16_f32 v104, v94, v95
	v_cvt_pk_bf16_f32 v105, v96, v97
	ds_bpermute_b32 v228, v216, v102
	ds_bpermute_b32 v229, v216, v103
	ds_bpermute_b32 v230, v216, v104
	ds_bpermute_b32 v231, v216, v105
	s_waitcnt lgkmcnt(4)
	s_nop 0
	global_store_dwordx4 v[220:221], v[224:227], off
	v_pk_mul_f32 v[98:99], v[98:99], v[132:133] op_sel_hi:[1,0]
	v_pk_mul_f32 v[100:101], v[100:101], v[132:133] op_sel_hi:[1,0]
	v_pk_mul_f32 v[90:91], v[90:91], v[132:133] op_sel_hi:[1,0]
	v_pk_mul_f32 v[92:93], v[92:93], v[132:133] op_sel_hi:[1,0]
	v_cvt_pk_bf16_f32 v98, v98, v99
	v_cvt_pk_bf16_f32 v99, v100, v101
	v_cvt_pk_bf16_f32 v100, v90, v91
	v_cvt_pk_bf16_f32 v101, v92, v93
	ds_bpermute_b32 v224, v216, v98
	ds_bpermute_b32 v225, v216, v99
	ds_bpermute_b32 v226, v216, v100
	ds_bpermute_b32 v227, v216, v101
	s_waitcnt lgkmcnt(4)
	s_nop 0
	global_store_dwordx4 v[220:221], v[228:231], off offset:256
	v_lshl_add_u64 v[220:221], v[220:221], 0, s[8:9]
	v_pk_mul_f32 v[86:87], v[86:87], v[132:133] op_sel_hi:[1,0]
	v_pk_mul_f32 v[88:89], v[88:89], v[132:133] op_sel_hi:[1,0]
	v_pk_mul_f32 v[78:79], v[78:79], v[132:133] op_sel_hi:[1,0]
	v_pk_mul_f32 v[80:81], v[80:81], v[132:133] op_sel_hi:[1,0]
	v_cvt_pk_bf16_f32 v86, v86, v87
	v_cvt_pk_bf16_f32 v87, v88, v89
	v_cvt_pk_bf16_f32 v88, v78, v79
	v_cvt_pk_bf16_f32 v89, v80, v81
	ds_bpermute_b32 v228, v216, v86
	ds_bpermute_b32 v229, v216, v87
	ds_bpermute_b32 v230, v216, v88
	ds_bpermute_b32 v231, v216, v89
	s_waitcnt lgkmcnt(4)
	s_nop 0
	global_store_dwordx4 v[220:221], v[224:227], off
	v_pk_mul_f32 v[82:83], v[82:83], v[142:143] op_sel_hi:[1,0]
	v_pk_mul_f32 v[84:85], v[84:85], v[142:143] op_sel_hi:[1,0]
	v_pk_mul_f32 v[74:75], v[74:75], v[142:143] op_sel_hi:[1,0]
	v_pk_mul_f32 v[76:77], v[76:77], v[142:143] op_sel_hi:[1,0]
	v_cvt_pk_bf16_f32 v82, v82, v83
	v_cvt_pk_bf16_f32 v83, v84, v85
	v_cvt_pk_bf16_f32 v84, v74, v75
	v_cvt_pk_bf16_f32 v85, v76, v77
	ds_bpermute_b32 v224, v216, v82
	ds_bpermute_b32 v225, v216, v83
	ds_bpermute_b32 v226, v216, v84
	ds_bpermute_b32 v227, v216, v85
	s_waitcnt lgkmcnt(4)
	s_nop 0
	global_store_dwordx4 v[220:221], v[228:231], off offset:256
	v_lshl_add_u64 v[220:221], v[220:221], 0, s[8:9]
	v_pk_mul_f32 v[70:71], v[70:71], v[142:143] op_sel_hi:[1,0]
	v_pk_mul_f32 v[72:73], v[72:73], v[142:143] op_sel_hi:[1,0]
	v_pk_mul_f32 v[66:67], v[66:67], v[142:143] op_sel_hi:[1,0]
	v_pk_mul_f32 v[68:69], v[68:69], v[142:143] op_sel_hi:[1,0]
	v_cvt_pk_bf16_f32 v70, v70, v71
	v_cvt_pk_bf16_f32 v71, v72, v73
	v_cvt_pk_bf16_f32 v72, v66, v67
	v_cvt_pk_bf16_f32 v73, v68, v69
	ds_bpermute_b32 v228, v216, v70
	ds_bpermute_b32 v229, v216, v71
	ds_bpermute_b32 v230, v216, v72
	ds_bpermute_b32 v231, v216, v73
	s_waitcnt lgkmcnt(4)
; __device__ __forceinline__ float sigm(float v) { return __builtin_amdgcn_rcpf(1.0f + __builtin_amdgcn_exp2f(-1.44269504089f * v)); }
; __device__ __forceinline__ u32x4 pack8(const f32x4& v0, const f32x4& v1) { u32x4 w; w.x = cvt_pk_bf16(v0[0], v0[1]); w.y = cvt_pk_bf16(v0[2], v0[3]); w.z = cvt_pk_bf16(v1[0], v1[1]); w.w = cvt_pk_bf16(v1[2], v1[3]); return w; }
; __device__ __forceinline__ float sumsq8(const f32x4& v0, const f32x4& v1) { return (v0[0] * v0[0] + v0[1] * v0[1]) + (v0[2] * v0[2] + v0[3] * v0[3]) + (v1[0] * v1[0] + v1[1] * v1[1]) + (v1[2] * v1[2] + v1[3] * v1[3]); }
; template <int ACT> __device__ __forceinline__ void epi_act_store(f32x4 (&acc)[2][2][4][2], const float (&rs)[2][4], bf16_t* out, int ld, int row0, int col0, float* ssqv_slot, bool want_ssq, int fq) {
;     ...
;         for (int m = 0; m < 4; ++m) { const int row = row0 + ai * 128 + m * 16; float sq = 0.f;
; #pragma unroll
;             for (int bj = 0; bj < 2; ++bj) { f32x4 v0 = acc[ai][bj][m][0] * rs[ai][m], v1 = acc[ai][bj][m][1] * rs[ai][m];
;                 if (ACT == 1) { f32x2 a = gelu_pk((f32x2){v0[0], v0[1]}), b = gelu_pk((f32x2){v0[2], v0[3]}), c = gelu_pk((f32x2){v1[0], v1[1]}), d = gelu_pk((f32x2){v1[2], v1[3]});
;                     v0 = (f32x4){a.x, a.y, b.x, b.y}; v1 = (f32x4){c.x, c.y, d.x, d.y}; sq += sumsq8(v0, v1); }
;                 if (ACT == 2) {
; #pragma unroll
;                     for (int e = 0; e < 4; ++e) { v0[e] = sigm(v0[e]); v1[e] = sigm(v1[e]); } }
;                 *(u32x4*)(out + (size_t)row * ld + col0 + bj * 128) = pack8(v0, v1); }
	s_nop 0
	global_store_dwordx4 v[220:221], v[224:227], off
	v_pk_mul_f32 v[62:63], v[62:63], v[140:141] op_sel_hi:[1,0]
	v_pk_mul_f32 v[64:65], v[64:65], v[140:141] op_sel_hi:[1,0]
	v_pk_mul_f32 v[58:59], v[58:59], v[140:141] op_sel_hi:[1,0]
	v_pk_mul_f32 v[60:61], v[60:61], v[140:141] op_sel_hi:[1,0]
	v_cvt_pk_bf16_f32 v62, v62, v63
	v_cvt_pk_bf16_f32 v63, v64, v65
	v_cvt_pk_bf16_f32 v64, v58, v59
	v_cvt_pk_bf16_f32 v65, v60, v61
	ds_bpermute_b32 v224, v216, v62
	ds_bpermute_b32 v225, v216, v63
	ds_bpermute_b32 v226, v216, v64
	ds_bpermute_b32 v227, v216, v65
	s_waitcnt lgkmcnt(4)
	s_nop 0
	global_store_dwordx4 v[220:221], v[228:231], off offset:256
	v_lshl_add_u64 v[220:221], v[220:221], 0, s[44:45]
	v_pk_mul_f32 v[54:55], v[54:55], v[140:141] op_sel_hi:[1,0]
	v_pk_mul_f32 v[56:57], v[56:57], v[140:141] op_sel_hi:[1,0]
	v_pk_mul_f32 v[50:51], v[50:51], v[140:141] op_sel_hi:[1,0]
	v_pk_mul_f32 v[52:53], v[52:53], v[140:141] op_sel_hi:[1,0]
	v_cvt_pk_bf16_f32 v54, v54, v55
	v_cvt_pk_bf16_f32 v55, v56, v57
	v_cvt_pk_bf16_f32 v56, v50, v51
	v_cvt_pk_bf16_f32 v57, v52, v53
	ds_bpermute_b32 v228, v216, v54
	ds_bpermute_b32 v229, v216, v55
	ds_bpermute_b32 v230, v216, v56
	ds_bpermute_b32 v231, v216, v57
	s_waitcnt lgkmcnt(4)
	s_nop 0
	global_store_dwordx4 v[220:221], v[224:227], off
	v_pk_mul_f32 v[46:47], v[46:47], v[138:139] op_sel_hi:[1,0]
	v_pk_mul_f32 v[48:49], v[48:49], v[138:139] op_sel_hi:[1,0]
	v_pk_mul_f32 v[42:43], v[42:43], v[138:139] op_sel_hi:[1,0]
	v_pk_mul_f32 v[44:45], v[44:45], v[138:139] op_sel_hi:[1,0]
	v_cvt_pk_bf16_f32 v46, v46, v47
	v_cvt_pk_bf16_f32 v47, v48, v49
	v_cvt_pk_bf16_f32 v48, v42, v43
	v_cvt_pk_bf16_f32 v49, v44, v45
	ds_bpermute_b32 v224, v216, v46
	ds_bpermute_b32 v225, v216, v47
	ds_bpermute_b32 v226, v216, v48
	ds_bpermute_b32 v227, v216, v49
	s_waitcnt lgkmcnt(4)
	s_nop 0
	global_store_dwordx4 v[220:221], v[228:231], off offset:256
	v_lshl_add_u64 v[220:221], v[220:221], 0, s[8:9]
	v_pk_mul_f32 v[38:39], v[38:39], v[138:139] op_sel_hi:[1,0]
	v_pk_mul_f32 v[40:41], v[40:41], v[138:139] op_sel_hi:[1,0]
	v_pk_mul_f32 v[34:35], v[34:35], v[138:139] op_sel_hi:[1,0]
	v_pk_mul_f32 v[36:37], v[36:37], v[138:139] op_sel_hi:[1,0]
	v_cvt_pk_bf16_f32 v38, v38, v39
	v_cvt_pk_bf16_f32 v39, v40, v41
	v_cvt_pk_bf16_f32 v40, v34, v35
	v_cvt_pk_bf16_f32 v41, v36, v37
	ds_bpermute_b32 v228, v216, v38
	ds_bpermute_b32 v229, v216, v39
	ds_bpermute_b32 v230, v216, v40
	ds_bpermute_b32 v231, v216, v41
	s_waitcnt lgkmcnt(4)
	s_nop 0
	global_store_dwordx4 v[220:221], v[224:227], off
	v_pk_mul_f32 v[30:31], v[30:31], v[134:135] op_sel_hi:[1,0]
	v_pk_mul_f32 v[32:33], v[32:33], v[134:135] op_sel_hi:[1,0]
	v_pk_mul_f32 v[26:27], v[26:27], v[134:135] op_sel_hi:[1,0]
	v_pk_mul_f32 v[28:29], v[28:29], v[134:135] op_sel_hi:[1,0]
	v_cvt_pk_bf16_f32 v30, v30, v31
	v_cvt_pk_bf16_f32 v31, v32, v33
	v_cvt_pk_bf16_f32 v32, v26, v27
	v_cvt_pk_bf16_f32 v33, v28, v29
	ds_bpermute_b32 v224, v216, v30
	ds_bpermute_b32 v225, v216, v31
	ds_bpermute_b32 v226, v216, v32
	ds_bpermute_b32 v227, v216, v33
	s_waitcnt lgkmcnt(4)
	s_nop 0
	global_store_dwordx4 v[220:221], v[228:231], off offset:256
	v_lshl_add_u64 v[220:221], v[220:221], 0, s[8:9]
	v_pk_mul_f32 v[22:23], v[22:23], v[134:135] op_sel_hi:[1,0]
	v_pk_mul_f32 v[24:25], v[24:25], v[134:135] op_sel_hi:[1,0]
	v_pk_mul_f32 v[18:19], v[18:19], v[134:135] op_sel_hi:[1,0]
	v_pk_mul_f32 v[20:21], v[20:21], v[134:135] op_sel_hi:[1,0]
	v_cvt_pk_bf16_f32 v22, v22, v23
	v_cvt_pk_bf16_f32 v23, v24, v25
	v_cvt_pk_bf16_f32 v24, v18, v19
	v_cvt_pk_bf16_f32 v25, v20, v21
	ds_bpermute_b32 v228, v216, v22
	ds_bpermute_b32 v229, v216, v23
	ds_bpermute_b32 v230, v216, v24
	ds_bpermute_b32 v231, v216, v25
	s_waitcnt lgkmcnt(4)
	s_nop 0
	global_store_dwordx4 v[220:221], v[224:227], off
	v_pk_mul_f32 v[14:15], v[14:15], v[136:137] op_sel_hi:[1,0]
	v_pk_mul_f32 v[16:17], v[16:17], v[136:137] op_sel_hi:[1,0]
	v_pk_mul_f32 v[10:11], v[10:11], v[136:137] op_sel_hi:[1,0]
	v_pk_mul_f32 v[12:13], v[12:13], v[136:137] op_sel_hi:[1,0]
	v_cvt_pk_bf16_f32 v14, v14, v15
	v_cvt_pk_bf16_f32 v15, v16, v17
	v_cvt_pk_bf16_f32 v16, v10, v11
	v_cvt_pk_bf16_f32 v17, v12, v13
	ds_bpermute_b32 v224, v216, v14
	ds_bpermute_b32 v225, v216, v15
	ds_bpermute_b32 v226, v216, v16
	ds_bpermute_b32 v227, v216, v17
	s_waitcnt lgkmcnt(4)
	s_nop 0
	global_store_dwordx4 v[220:221], v[228:231], off offset:256
	v_lshl_add_u64 v[220:221], v[220:221], 0, s[8:9]
	v_pk_mul_f32 v[6:7], v[6:7], v[136:137] op_sel_hi:[1,0]
	v_pk_mul_f32 v[8:9], v[8:9], v[136:137] op_sel_hi:[1,0]
	v_pk_mul_f32 v[2:3], v[2:3], v[136:137] op_sel_hi:[1,0]
	v_pk_mul_f32 v[4:5], v[4:5], v[136:137] op_sel_hi:[1,0]
	v_cvt_pk_bf16_f32 v6, v6, v7
	v_cvt_pk_bf16_f32 v7, v8, v9
	v_cvt_pk_bf16_f32 v8, v2, v3
	v_cvt_pk_bf16_f32 v9, v4, v5
	ds_bpermute_b32 v228, v216, v6
	ds_bpermute_b32 v229, v216, v7
	ds_bpermute_b32 v230, v216, v8
	ds_bpermute_b32 v231, v216, v9
	s_waitcnt lgkmcnt(4)
	s_nop 0
	global_store_dwordx4 v[220:221], v[224:227], off
	s_waitcnt lgkmcnt(0)
	s_nop 0
	global_store_dwordx4 v[220:221], v[228:231], off offset:256
